# half of each XCD's workgroups start the residual-epilogue GEMM phases (DN, OUT) about 1.5 us late, to split the epilogue load/store bursts
# speedup vs baseline: 1.0026x; 1.0004x over previous
.LBB0_247:
	s_waitcnt lgkmcnt(0)
	s_barrier
	s_bitcmp1_b32 s2, 3
	s_cbranch_scc0 .Lstag_0
	s_sleep 48
.Lstag_0:
.LBB0_248:
	s_cmp_lt_i32 s60, 3
	s_cselect_b64 s[6:7], -1, 0
	s_and_b64 s[74:75], s[6:7], s[10:11]
	s_andn2_b64 vcc, exec, s[74:75]
	s_cbranch_vccnz .LBB0_295
	s_cmpk_lt_i32 s2, 0x200
	s_cselect_b64 s[6:7], -1, 0
	s_cmpk_gt_i32 s2, 0x1ff
	v_readfirstlane_b32 s10, v240
	s_cbranch_scc1 .LBB0_255
	s_ashr_i32 s3, s2, 31
	s_lshr_b32 s3, s3, 29
	s_add_i32 s3, s2, s3
	s_and_b32 s8, s3, -8
	s_sub_i32 s11, s2, s8
	s_cmp_gt_i32 s11, -1
	s_cbranch_scc0 .LBB0_252
	s_lshl_b32 s14, s11, 6
	s_cbranch_execz .LBB0_253
	s_branch .LBB0_254

.Lstag_4:
.LBB0_973:
	s_cmp_lt_i32 s60, 7
	s_cselect_b64 s[4:5], -1, 0
	s_and_b64 s[8:9], s[4:5], s[6:7]
	s_andn2_b64 vcc, exec, s[8:9]
	s_cbranch_vccnz .LBB0_1016
	s_cmpk_lt_i32 s2, 0x200
	s_cselect_b64 s[4:5], -1, 0
	s_cmpk_gt_i32 s2, 0x1ff
	v_readfirstlane_b32 s23, v240
	s_cbranch_scc1 .LBB0_980
	s_ashr_i32 s3, s2, 31
	s_lshr_b32 s3, s3, 29
	s_add_i32 s3, s2, s3
	s_and_b32 s6, s3, -8
	s_sub_i32 s10, s2, s6
	s_cmp_gt_i32 s10, -1
	s_cbranch_scc0 .LBB0_977
	s_lshl_b32 s11, s10, 6
	s_cbranch_execz .LBB0_978
	s_branch .LBB0_979

.Lstag_6:
.LBB0_1275:
	s_cmp_lt_i32 s60, 9
	s_cselect_b64 s[4:5], -1, 0
	s_and_b64 s[10:11], s[4:5], s[8:9]
	s_andn2_b64 vcc, exec, s[10:11]
	s_cbranch_vccnz .LBB0_1322
	s_cmpk_lt_i32 s2, 0x200
	s_cselect_b64 s[4:5], -1, 0
	s_cmpk_gt_i32 s2, 0x1ff
	v_readfirstlane_b32 s8, v240
	s_cbranch_scc1 .LBB0_1282
	s_ashr_i32 s3, s2, 31
	s_lshr_b32 s3, s3, 29
	s_add_i32 s3, s2, s3
	s_and_b32 s6, s3, -8
	s_sub_i32 s9, s2, s6
	s_cmp_gt_i32 s9, -1
	s_cbranch_scc0 .LBB0_1279
	s_lshl_b32 s14, s9, 6
	s_cbranch_execz .LBB0_1280
	s_branch .LBB0_1281

.Lstag_8:
.LBB0_1581:
	s_cmp_lt_i32 s60, 11
	s_cselect_b64 s[4:5], -1, 0
	s_and_b64 s[10:11], s[4:5], s[8:9]
	s_andn2_b64 vcc, exec, s[10:11]
	s_cbranch_vccnz .LBB0_1628
	s_cmpk_lt_i32 s2, 0x200
	s_cselect_b64 s[4:5], -1, 0
	s_cmpk_gt_i32 s2, 0x1ff
	v_readfirstlane_b32 s8, v240
	s_cbranch_scc1 .LBB0_1588
	s_ashr_i32 s3, s2, 31
	s_lshr_b32 s3, s3, 29
	s_add_i32 s3, s2, s3
	s_and_b32 s6, s3, -8
	s_sub_i32 s9, s2, s6
	s_cmp_gt_i32 s9, -1
	s_cbranch_scc0 .LBB0_1585
	s_lshl_b32 s14, s9, 6
	s_cbranch_execz .LBB0_1586
	s_branch .LBB0_1587

.Lstag_11:
.LBB0_2017:
	s_cmp_lt_i32 s60, 14
	s_cselect_b64 s[4:5], -1, 0
	s_and_b64 s[8:9], s[4:5], s[6:7]
	s_andn2_b64 vcc, exec, s[8:9]
	s_cbranch_vccnz .LBB0_2060
	s_cmpk_lt_i32 s2, 0x200
	s_cselect_b64 s[4:5], -1, 0
	s_cmpk_gt_i32 s2, 0x1ff
	v_readfirstlane_b32 s23, v240
	s_cbranch_scc1 .LBB0_2024
	s_ashr_i32 s3, s2, 31
	s_lshr_b32 s3, s3, 29
	s_add_i32 s3, s2, s3
	s_and_b32 s6, s3, -8
	s_sub_i32 s10, s2, s6
	s_cmp_gt_i32 s10, -1
	s_cbranch_scc0 .LBB0_2021
	s_lshl_b32 s11, s10, 6
	s_cbranch_execz .LBB0_2022
	s_branch .LBB0_2023

.Lstag_13:
.LBB0_2319:
	v_readlane_b32 s0, v254, 49
	v_readlane_b32 s1, v254, 50
	s_cmp_lt_i32 s0, 16
	s_cselect_b64 s[0:1], -1, 0
	s_and_b64 s[0:1], s[0:1], s[8:9]
	s_andn2_b64 vcc, exec, s[0:1]
	s_cbranch_vccnz .LBB0_2348
	s_cmpk_gt_i32 s2, 0x1ff
	v_readfirstlane_b32 s4, v240
	s_cbranch_scc1 .LBB0_2348
	s_ashr_i32 s3, s2, 31
	s_lshr_b32 s0, s3, 29
	s_add_i32 s7, s2, s0
	s_and_b32 s0, s7, -8
	s_sub_i32 s5, s2, s0
	s_cmp_gt_i32 s5, -1
	s_cbranch_scc0 .LBB0_2323
	s_lshl_b32 s6, s5, 6
	s_ashr_i32 s1, s7, 3
	s_cbranch_execz .LBB0_2324
	s_branch .LBB0_2325
